# GEMM cold prologue de-serialised: second batch of 6 LDS-DMA loads issued before the first counted wait (vmcnt(2)->vmcnt(8))
# speedup vs baseline: 1.0011x; 1.0011x over previous
; #define PG8_STAGE(bufoff, gbase, voff) do { _Pragma("unroll") for (int _i = 0; _i < 2; ++_i) \
;         __builtin_amdgcn_global_load_lds((const unsigned*)((const char*)(gbase) + (voff)[_i]), (PG8_LAS unsigned*)(lds + (bufoff) + ldsw + _i * 8192), 16, 0, 0); } while (0)
; #define PG8_WAIT_V(n) asm volatile("s_waitcnt vmcnt(" #n ")" ::: "memory")
; #define PG8_BAR __builtin_amdgcn_s_barrier()
; template <class Epi, class Sched, bool ALIGN_EPI = false, bool SP2 = false>
; __device__ __forceinline__ void gemm_phase(PG8_LAS unsigned char* lds, const Gemm g, const Sched& S, const Epi& E, const int tid) {
;     ...
;         PG8_STAGE(PG8_SB(0, 0), cB, voffB); PG8_STAGE(PG8_SB(0, 1), cB + hstep, voffB); PG8_STAGE(PG8_SA(0, 0), cA, voffA); PG8_STAGE(PG8_SA(0, 1), cA + hstep, voffA);
;         if (wr == 1) PG8_BAR;
;         PG8_WAIT_V(2); PG8_BAR;
;         PG8_STAGE(PG8_SB(1, 0), cB + kstep, voffB); PG8_STAGE(PG8_SA(1, 0), cA + kstep, voffA); PG8_STAGE(PG8_SB(1, 1), cB + hstep + kstep, voffB);
;         PG8_WAIT_V(6); PG8_BAR;
.LBB0_93:
	v_lshrrev_b32_e32 v18, 1, v164
	s_add_u32 s6, s90, 0xb088000
	v_and_b32_e32 v18, 24, v18
	s_addc_u32 s7, s91, 0
	v_lshl_or_b32 v3, s8, 6, v19
	v_lshlrev_b32_e32 v20, 1, v18
	v_lshlrev_b32_e32 v21, 6, v19
	s_movk_i32 s9, 0x3c0
	v_lshlrev_b32_e32 v19, 2, v19
	s_lshl_b32 s3, s3, 5
	v_and_or_b32 v22, v21, s9, v20
	s_lshl_b32 s8, s8, 13
	v_and_b32_e32 v19, 32, v19
	s_and_b32 s3, s3, 0x60
	s_add_i32 m0, s36, 0x18000
	v_lshl_add_u64 v[10:11], v[10:11], 0, s[0:1]
	v_bitop3_b32 v22, v22, s8, v19 bitop3:0xde
	v_or_b32_e32 v20, v20, v21
	s_lshl_b32 s8, s3, 7
	global_load_lds_dwordx4 v[10:11], off
	v_lshl_add_u64 v[8:9], v[8:9], 0, s[0:1]
	s_add_i32 m0, s36, 0x1a000
	s_add_i32 s40, s36, 0x8000
	s_add_i32 s41, s36, 0xa000
	v_bitop3_b32 v153, s8, v20, v19 bitop3:0xf6
	global_load_lds_dwordx4 v[8:9], off
	v_lshl_add_u64 v[4:5], v[4:5], 0, s[0:1]
	s_mov_b32 m0, s40
	s_add_u32 s8, s20, 0x40080
	global_load_lds_dwordx4 v[4:5], off
	v_lshl_add_u64 v[4:5], v[6:7], 0, s[0:1]
	s_mov_b32 m0, s41
	s_addc_u32 s9, s21, 0
	global_load_lds_dwordx4 v[4:5], off
	s_add_i32 m0, s36, 0x1c000
	v_lshl_add_u64 v[4:5], s[8:9], 0, v[168:169]
	global_load_lds_dwordx4 v[4:5], off
	v_lshl_add_u64 v[4:5], s[8:9], 0, v[0:1]
	s_add_i32 m0, s36, 0x1e000
	s_cmpk_lt_u32 s2, 0x100
	global_load_lds_dwordx4 v[4:5], off
	s_waitcnt vmcnt(8)
	s_barrier
	v_lshlrev_b32_e32 v4, 14, v16
	v_and_b32_e32 v4, 0xffff8000, v4
	v_lshl_add_u32 v4, v15, 11, v4
	v_and_b32_e32 v5, 1, v16
	v_lshl_or_b32 v4, v5, 6, v4
	v_lshl_add_u32 v172, v17, 1, v4
	v_lshlrev_b32_e32 v4, 14, v12
	v_and_b32_e32 v4, 0xffff8000, v4
	s_waitcnt vmcnt(6)
	v_lshl_add_u32 v4, v13, 11, v4
	v_and_b32_e32 v5, 1, v12
	v_or_b32_e32 v165, s3, v18
	v_lshl_or_b32 v4, v5, 6, v4
	v_readlane_b32 s2, v253, 5
	s_cselect_b64 s[8:9], -1, 0
	v_mov_b32_e32 v173, v2
	v_lshl_add_u32 v174, v14, 1, v4
	v_mov_b32_e32 v175, v2
	s_mov_b32 s42, 0
	v_add_u32_e32 v176, 0, v22
	v_readlane_b32 s44, v253, 2
	s_mov_b32 s43, s2
	s_barrier
	v_readlane_b32 s3, v253, 6
	s_branch .LBB0_96

; #define PG8_STAGE(bufoff, gbase, voff) do { _Pragma("unroll") for (int _i = 0; _i < 2; ++_i) \
;         __builtin_amdgcn_global_load_lds((const unsigned*)((const char*)(gbase) + (voff)[_i]), (PG8_LAS unsigned*)(lds + (bufoff) + ldsw + _i * 8192), 16, 0, 0); } while (0)
; #define PG8_WAIT_V(n) asm volatile("s_waitcnt vmcnt(" #n ")" ::: "memory")
; #define PG8_BAR __builtin_amdgcn_s_barrier()
; template <class Epi, class Sched, bool ALIGN_EPI = false, bool SP2 = false>
; __device__ __forceinline__ void gemm_phase(PG8_LAS unsigned char* lds, const Gemm g, const Sched& S, const Epi& E, const int tid) {
;     ...
;     for (int i = 0; i < 2; ++i) { int R, C; stage_rc(tid * 16 + i * 8192, R, C); const int Rb = Epi::PERM ? ((R & ~31) + perm32(R & 31)) : R;
;         voffA[i] = (unsigned)(R * K + C) * 2u; voffB[i] = (unsigned)(Rb * K + C) * 2u; }
;     const size_t kstep = (size_t)(BK * 2);
;     const size_t hstep = (size_t)HALF * K * 2;
;     const size_t tstep = 2 * hstep;
;     const unsigned ldsw = (unsigned)wid * 1024u;
;     const int aoff = lds_byte(wr * 64 + fr, fq * 8), boff = lds_byte(wc * 32 + fr, fq * 8);
;     ...
;     if constexpr (SP2) {
;         PG8_STAGE(PG8_SB(0, 0), cB, voffB); PG8_STAGE(PG8_SB(0, 1), cB + hstep, voffB); PG8_STAGE(PG8_SA(0, 0), cA, voffA); PG8_STAGE(PG8_SA(0, 1), cA + hstep, voffA);
;         if (wr == 1) PG8_BAR;
;         PG8_WAIT_V(2); PG8_BAR;
;         PG8_STAGE(PG8_SB(1, 0), cB + kstep, voffB); PG8_STAGE(PG8_SA(1, 0), cA + kstep, voffA); PG8_STAGE(PG8_SB(1, 1), cB + hstep + kstep, voffB);
;         PG8_WAIT_V(6); PG8_BAR;
.LBB0_282:
	v_lshrrev_b32_e32 v18, 1, v164
	v_and_b32_e32 v18, 24, v18
	s_add_u32 s8, s90, 0x1464000
	v_and_b32_e32 v3, 15, v164
	v_lshlrev_b32_e32 v19, 1, v18
	v_lshlrev_b32_e32 v20, 2, v164
	s_addc_u32 s9, s91, 0
	s_and_b32 s14, s5, 3
	v_lshl_or_b32 v19, v3, 6, v19
	s_lshl_b32 s5, s10, 13
	v_and_b32_e32 v20, 32, v20
	s_add_i32 m0, s25, 0x18000
	v_lshl_add_u64 v[10:11], v[10:11], 0, s[0:1]
	s_lshl_b32 s47, s10, 6
	v_bitop3_b32 v21, v19, s5, v20 bitop3:0xde
	s_lshl_b32 s5, s14, 12
	global_load_lds_dwordx4 v[10:11], off
	v_lshl_add_u64 v[8:9], v[8:9], 0, s[0:1]
	s_add_i32 m0, s25, 0x1a000
	s_add_i32 s48, s25, 0x8000
	s_add_i32 s49, s25, 0xa000
	global_load_lds_dwordx4 v[8:9], off
	v_lshl_add_u64 v[4:5], v[4:5], 0, s[0:1]
	s_mov_b32 m0, s48
	s_add_u32 s10, s26, 0x40080
	global_load_lds_dwordx4 v[4:5], off
	v_lshl_add_u64 v[4:5], v[6:7], 0, s[0:1]
	s_mov_b32 m0, s49
	s_addc_u32 s11, s27, 0
	global_load_lds_dwordx4 v[4:5], off
	s_add_i32 m0, s25, 0x1c000
	v_lshl_add_u64 v[4:5], s[10:11], 0, v[132:133]
	global_load_lds_dwordx4 v[4:5], off
	v_lshl_add_u64 v[4:5], s[10:11], 0, v[136:137]
	s_add_i32 m0, s25, 0x1e000
	v_readlane_b32 s52, v251, 16
	global_load_lds_dwordx4 v[4:5], off
	s_waitcnt vmcnt(8)
	s_barrier
	v_lshlrev_b32_e32 v4, 2, v18
	v_mov_b32_e32 v5, v2
	v_readlane_b32 s54, v251, 18
	v_readlane_b32 s55, v251, 19
	v_lshl_add_u64 v[6:7], s[90:91], 0, v[4:5]
	s_waitcnt vmcnt(6)
	s_cmpk_lt_u32 s4, 0x100
	v_lshl_add_u64 v[140:141], s[54:55], 0, v[4:5]
	v_lshlrev_b32_e32 v4, 14, v12
	v_and_b32_e32 v4, 0xffff8000, v4
	v_lshl_add_u32 v4, v13, 11, v4
	v_and_b32_e32 v5, 1, v12
	v_lshl_or_b32 v4, v5, 6, v4
	v_lshl_add_u32 v142, v14, 1, v4
	v_lshlrev_b32_e32 v4, 14, v15
	v_and_b32_e32 v4, 0xffff8000, v4
	v_lshl_add_u32 v4, v16, 11, v4
	v_and_b32_e32 v5, 1, v15
	v_bitop3_b32 v165, s5, v19, v20 bitop3:0xf6
	s_cselect_b64 s[10:11], -1, 0
	s_cmp_eq_u32 s14, 0
	s_mov_b64 s[4:5], 0xc24000
	v_readlane_b32 s59, v251, 23
	v_readlane_b32 s60, v251, 24
	v_lshl_or_b32 v4, v5, 6, v4
	s_mov_b32 s50, 0
	s_cselect_b64 s[12:13], -1, 0
	v_lshl_add_u64 v[138:139], v[6:7], 0, s[4:5]
	v_lshl_or_b32 v170, s14, 5, v18
	v_mov_b32_e32 v143, v2
	v_lshl_add_u32 v144, v17, 1, v4
	v_mov_b32_e32 v145, v2
	v_add_u32_e32 v171, 0, v21
	s_movk_i32 s59, 0xc00
	s_movk_i32 s60, 0x7d
	s_barrier
	v_readlane_b32 s53, v251, 17
	v_readlane_b32 s56, v251, 20
	v_readlane_b32 s57, v251, 21
	v_readlane_b32 s58, v251, 22
	v_readlane_b32 s61, v251, 25
	v_readlane_b32 s62, v251, 26
	v_readlane_b32 s63, v251, 27
	v_readlane_b32 s64, v251, 28
	v_readlane_b32 s65, v251, 29
	v_readlane_b32 s66, v251, 30
	v_readlane_b32 s67, v251, 31
	s_branch .LBB0_286

; #define PG8_STAGE(bufoff, gbase, voff) do { _Pragma("unroll") for (int _i = 0; _i < 2; ++_i) \
;         __builtin_amdgcn_global_load_lds((const unsigned*)((const char*)(gbase) + (voff)[_i]), (PG8_LAS unsigned*)(lds + (bufoff) + ldsw + _i * 8192), 16, 0, 0); } while (0)
; #define PG8_WAIT_V(n) asm volatile("s_waitcnt vmcnt(" #n ")" ::: "memory")
; #define PG8_BAR __builtin_amdgcn_s_barrier()
; template <class Epi, class Sched, bool ALIGN_EPI = false, bool SP2 = false>
; __device__ __forceinline__ void gemm_phase(PG8_LAS unsigned char* lds, const Gemm g, const Sched& S, const Epi& E, const int tid) {
;     ...
;     for (int i = 0; i < 2; ++i) { int R, C; stage_rc(tid * 16 + i * 8192, R, C); const int Rb = Epi::PERM ? ((R & ~31) + perm32(R & 31)) : R;
;         voffA[i] = (unsigned)(R * K + C) * 2u; voffB[i] = (unsigned)(Rb * K + C) * 2u; }
;     const size_t kstep = (size_t)(BK * 2);
;     const size_t hstep = (size_t)HALF * K * 2;
;     const size_t tstep = 2 * hstep;
;     const unsigned ldsw = (unsigned)wid * 1024u;
;     const int aoff = lds_byte(wr * 64 + fr, fq * 8), boff = lds_byte(wc * 32 + fr, fq * 8);
;     ...
;     if constexpr (SP2) {
;         PG8_STAGE(PG8_SB(0, 0), cB, voffB); PG8_STAGE(PG8_SB(0, 1), cB + hstep, voffB); PG8_STAGE(PG8_SA(0, 0), cA, voffA); PG8_STAGE(PG8_SA(0, 1), cA + hstep, voffA);
;         if (wr == 1) PG8_BAR;
;         PG8_WAIT_V(2); PG8_BAR;
;         PG8_STAGE(PG8_SB(1, 0), cB + kstep, voffB); PG8_STAGE(PG8_SA(1, 0), cA + kstep, voffA); PG8_STAGE(PG8_SB(1, 1), cB + hstep + kstep, voffB);
;         PG8_WAIT_V(6); PG8_BAR;
.LBB0_464:
	s_add_i32 m0, s62, 0x18000
	v_lshl_add_u64 v[8:9], v[8:9], 0, s[0:1]
	global_load_lds_dwordx4 v[8:9], off
	v_lshl_add_u64 v[8:9], v[10:11], 0, s[0:1]
	s_add_i32 m0, s62, 0x1a000
	s_add_i32 s66, s62, 0x8000
	global_load_lds_dwordx4 v[8:9], off
	v_lshl_add_u64 v[8:9], v[14:15], 0, s[0:1]
	s_mov_b32 m0, s66
	s_add_i32 s67, s62, 0xa000
	global_load_lds_dwordx4 v[8:9], off
	v_lshl_add_u64 v[8:9], v[12:13], 0, s[0:1]
	s_mov_b32 m0, s67
	v_lshl_add_u64 v[4:5], v[4:5], 0, s[0:1]
	global_load_lds_dwordx4 v[8:9], off
	s_add_i32 m0, s62, 0x1c000
	s_lshr_b32 s69, s37, 6
	global_load_lds_dwordx4 v[4:5], off
	v_lshl_add_u64 v[4:5], v[6:7], 0, s[0:1]
	s_add_i32 m0, s62, 0x1e000
	s_and_b32 s68, s5, 3
	global_load_lds_dwordx4 v[4:5], off
	s_waitcnt vmcnt(8)
	s_barrier
	v_lshl_or_b32 v183, s4, 6, v3
	s_lshl_b32 s4, s4, 13
	s_add_i32 s70, s69, -2
	s_cmpk_lt_u32 s50, 0x100
	v_lshlrev_b32_e32 v5, 2, v3
	s_cselect_b64 s[50:51], -1, 0
	s_lshr_b32 s71, s36, 3
	v_lshl_or_b32 v4, v3, 6, v165
	v_and_b32_e32 v5, 32, v5
	s_waitcnt vmcnt(6)
	s_and_b32 s72, s36, 7
	s_add_i32 s73, s71, 1
	v_bitop3_b32 v4, v4, s4, v5 bitop3:0xde
	s_cmp_lg_u64 s[40:41], 0
	v_lshl_or_b32 v184, s68, 12, v182
	v_lshl_or_b32 v185, s68, 5, v153
	s_mov_b32 s37, s35
	s_mov_b32 s74, 0
	s_cselect_b64 s[52:53], -1, 0
	v_add_u32_e32 v186, 0, v4
	s_barrier
	s_branch .LBB0_467

; #define PG8_STAGE(bufoff, gbase, voff) do { _Pragma("unroll") for (int _i = 0; _i < 2; ++_i) \
;         __builtin_amdgcn_global_load_lds((const unsigned*)((const char*)(gbase) + (voff)[_i]), (PG8_LAS unsigned*)(lds + (bufoff) + ldsw + _i * 8192), 16, 0, 0); } while (0)
; #define PG8_WAIT_V(n) asm volatile("s_waitcnt vmcnt(" #n ")" ::: "memory")
; #define PG8_BAR __builtin_amdgcn_s_barrier()
; template <class Epi, class Sched, bool ALIGN_EPI = false, bool SP2 = false>
; __device__ __forceinline__ void gemm_phase(PG8_LAS unsigned char* lds, const Gemm g, const Sched& S, const Epi& E, const int tid) {
;     ...
;     for (int i = 0; i < 2; ++i) { int R, C; stage_rc(tid * 16 + i * 8192, R, C); const int Rb = Epi::PERM ? ((R & ~31) + perm32(R & 31)) : R;
;         voffA[i] = (unsigned)(R * K + C) * 2u; voffB[i] = (unsigned)(Rb * K + C) * 2u; }
;     const size_t kstep = (size_t)(BK * 2);
;     const size_t hstep = (size_t)HALF * K * 2;
;     const size_t tstep = 2 * hstep;
;     const unsigned ldsw = (unsigned)wid * 1024u;
;     const int aoff = lds_byte(wr * 64 + fr, fq * 8), boff = lds_byte(wc * 32 + fr, fq * 8);
;     ...
;     if constexpr (SP2) {
;         PG8_STAGE(PG8_SB(0, 0), cB, voffB); PG8_STAGE(PG8_SB(0, 1), cB + hstep, voffB); PG8_STAGE(PG8_SA(0, 0), cA, voffA); PG8_STAGE(PG8_SA(0, 1), cA + hstep, voffA);
;         if (wr == 1) PG8_BAR;
;         PG8_WAIT_V(2); PG8_BAR;
;         PG8_STAGE(PG8_SB(1, 0), cB + kstep, voffB); PG8_STAGE(PG8_SA(1, 0), cA + kstep, voffA); PG8_STAGE(PG8_SB(1, 1), cB + hstep + kstep, voffB);
;         PG8_WAIT_V(6); PG8_BAR;
.LBB0_516:
	v_lshrrev_b32_e32 v19, 1, v164
	v_and_b32_e32 v19, 24, v19
	v_mov_b32_e32 v135, v2
	v_and_b32_e32 v18, 15, v164
	v_lshlrev_b32_e32 v20, 1, v19
	v_lshl_add_u64 v[10:11], s[20:21], 0, v[134:135]
	v_mov_b32_e32 v1, v2
	v_lshl_or_b32 v3, s8, 6, v18
	v_lshl_or_b32 v18, v18, 6, v20
	v_lshlrev_b32_e32 v20, 2, v164
	s_lshl_b32 s3, s3, 5
	v_lshl_add_u64 v[12:13], s[20:21], 0, v[0:1]
	v_mov_b32_e32 v137, v2
	s_lshl_b32 s8, s8, 13
	v_and_b32_e32 v20, 32, v20
	s_and_b32 s3, s3, 0x60
	s_add_i32 m0, s38, 0x18000
	v_lshl_add_u64 v[10:11], v[10:11], 0, s[0:1]
	v_lshl_add_u64 v[14:15], s[18:19], 0, v[136:137]
	v_mov_b32_e32 v133, v2
	v_bitop3_b32 v21, v18, s8, v20 bitop3:0xde
	s_lshl_b32 s8, s3, 7
	global_load_lds_dwordx4 v[10:11], off
	v_lshl_add_u64 v[10:11], v[12:13], 0, s[0:1]
	s_add_i32 m0, s38, 0x1a000
	s_add_i32 s42, s38, 0x8000
	s_add_i32 s43, s38, 0xa000
	v_lshl_add_u64 v[16:17], s[18:19], 0, v[132:133]
	v_bitop3_b32 v146, s8, v18, v20 bitop3:0xf6
	global_load_lds_dwordx4 v[10:11], off
	v_lshl_add_u64 v[10:11], v[14:15], 0, s[0:1]
	s_mov_b32 m0, s42
	s_add_u32 s8, s20, 0x40080
	global_load_lds_dwordx4 v[10:11], off
	v_lshl_add_u64 v[10:11], v[16:17], 0, s[0:1]
	s_mov_b32 m0, s43
	s_addc_u32 s9, s21, 0
	global_load_lds_dwordx4 v[10:11], off
	s_add_i32 m0, s38, 0x1c000
	v_lshl_add_u64 v[10:11], s[8:9], 0, v[134:135]
	global_load_lds_dwordx4 v[10:11], off
	v_lshl_add_u64 v[10:11], s[8:9], 0, v[0:1]
	s_add_i32 m0, s38, 0x1e000
	s_cmpk_lt_u32 s2, 0x100
	global_load_lds_dwordx4 v[10:11], off
	s_waitcnt vmcnt(8)
	s_barrier
	v_lshlrev_b32_e32 v10, 14, v8
	v_and_b32_e32 v10, 0xffff8000, v10
	v_lshl_add_u32 v7, v7, 11, v10
	v_and_b32_e32 v8, 1, v8
	v_lshl_or_b32 v7, v8, 6, v7
	v_lshl_add_u32 v138, v9, 1, v7
	v_lshlrev_b32_e32 v7, 14, v4
	v_and_b32_e32 v7, 0xffff8000, v7
	s_waitcnt vmcnt(6)
	v_lshl_add_u32 v5, v5, 11, v7
	v_and_b32_e32 v4, 1, v4
	v_or_b32_e32 v147, s3, v19
	v_lshl_or_b32 v4, v4, 6, v5
	v_readlane_b32 s2, v253, 12
	s_cselect_b64 s[8:9], -1, 0
	v_mov_b32_e32 v139, v2
	v_lshl_add_u32 v140, v6, 1, v4
	v_mov_b32_e32 v141, v2
	s_mov_b32 s44, 0
	v_add_u32_e32 v153, 0, v21
	v_readlane_b32 s45, v253, 17
	s_mov_b32 s46, s2
	s_movk_i32 s55, 0x16c
	s_movk_i32 s56, 0x1600
	s_barrier
	v_readlane_b32 s3, v253, 13
	s_branch .LBB0_519

; #define PG8_STAGE(bufoff, gbase, voff) do { _Pragma("unroll") for (int _i = 0; _i < 2; ++_i) \
;         __builtin_amdgcn_global_load_lds((const unsigned*)((const char*)(gbase) + (voff)[_i]), (PG8_LAS unsigned*)(lds + (bufoff) + ldsw + _i * 8192), 16, 0, 0); } while (0)
; #define PG8_WAIT_V(n) asm volatile("s_waitcnt vmcnt(" #n ")" ::: "memory")
; #define PG8_BAR __builtin_amdgcn_s_barrier()
; template <class Epi, class Sched, bool ALIGN_EPI = false, bool SP2 = false>
; __device__ __forceinline__ void gemm_phase(PG8_LAS unsigned char* lds, const Gemm g, const Sched& S, const Epi& E, const int tid) {
;     ...
;     for (int i = 0; i < 2; ++i) { int R, C; stage_rc(tid * 16 + i * 8192, R, C); const int Rb = Epi::PERM ? ((R & ~31) + perm32(R & 31)) : R;
;         voffA[i] = (unsigned)(R * K + C) * 2u; voffB[i] = (unsigned)(Rb * K + C) * 2u; }
;     const size_t kstep = (size_t)(BK * 2);
;     const size_t hstep = (size_t)HALF * K * 2;
;     const size_t tstep = 2 * hstep;
;     const unsigned ldsw = (unsigned)wid * 1024u;
;     const int aoff = lds_byte(wr * 64 + fr, fq * 8), boff = lds_byte(wc * 32 + fr, fq * 8);
;     ...
;     if constexpr (SP2) {
;         PG8_STAGE(PG8_SB(0, 0), cB, voffB); PG8_STAGE(PG8_SB(0, 1), cB + hstep, voffB); PG8_STAGE(PG8_SA(0, 0), cA, voffA); PG8_STAGE(PG8_SA(0, 1), cA + hstep, voffA);
;         if (wr == 1) PG8_BAR;
;         PG8_WAIT_V(2); PG8_BAR;
;         PG8_STAGE(PG8_SB(1, 0), cB + kstep, voffB); PG8_STAGE(PG8_SA(1, 0), cA + kstep, voffA); PG8_STAGE(PG8_SB(1, 1), cB + hstep + kstep, voffB);
;         PG8_WAIT_V(6); PG8_BAR;
.LBB0_836:
	s_add_u32 s6, s90, 0x84000
	s_addc_u32 s7, s91, 0
	s_lshl_b32 s10, s10, 5
	s_and_b32 s13, s10, 0x60
	s_add_i32 m0, s21, 0x18000
	v_lshl_add_u64 v[10:11], v[10:11], 0, s[0:1]
	s_lshl_b32 s12, s9, 13
	s_lshl_b32 s14, s13, 7
	global_load_lds_dwordx4 v[10:11], off
	v_lshl_add_u64 v[8:9], v[8:9], 0, s[0:1]
	s_add_i32 m0, s21, 0x1a000
	s_add_i32 s43, s21, 0x8000
	s_add_i32 s44, s21, 0xa000
	global_load_lds_dwordx4 v[8:9], off
	v_lshl_add_u64 v[4:5], v[4:5], 0, s[0:1]
	s_mov_b32 m0, s43
	s_add_u32 s10, s24, 0x40080
	global_load_lds_dwordx4 v[4:5], off
	v_lshl_add_u64 v[4:5], v[6:7], 0, s[0:1]
	s_mov_b32 m0, s44
	s_addc_u32 s11, s25, 0
	global_load_lds_dwordx4 v[4:5], off
	s_add_i32 m0, s21, 0x1c000
	v_lshl_add_u64 v[4:5], s[10:11], 0, v[132:133]
	global_load_lds_dwordx4 v[4:5], off
	v_lshl_add_u64 v[4:5], s[10:11], 0, v[136:137]
	s_add_i32 m0, s21, 0x1e000
	s_cmpk_lt_u32 s8, 0x100
	global_load_lds_dwordx4 v[4:5], off
	s_waitcnt vmcnt(8)
	s_barrier
	v_lshrrev_b32_e32 v5, 1, v164
	v_and_b32_e32 v5, 24, v5
	v_and_b32_e32 v4, 15, v164
	v_lshlrev_b32_e32 v6, 1, v5
	v_lshl_or_b32 v3, s9, 6, v4
	v_lshl_or_b32 v4, v4, 6, v6
	v_lshlrev_b32_e32 v6, 2, v164
	v_and_b32_e32 v6, 32, v6
	v_bitop3_b32 v7, v4, s12, v6 bitop3:0xde
	v_bitop3_b32 v146, s14, v4, v6 bitop3:0xf6
	v_lshlrev_b32_e32 v4, 14, v12
	v_and_b32_e32 v4, 0xffff8000, v4
	v_or_b32_e32 v147, s13, v5
	v_lshl_add_u32 v4, v13, 11, v4
	v_and_b32_e32 v5, 1, v12
	v_lshl_or_b32 v4, v5, 6, v4
	v_lshl_add_u32 v138, v14, 1, v4
	v_lshlrev_b32_e32 v4, 14, v15
	v_and_b32_e32 v4, 0xffff8000, v4
	s_waitcnt vmcnt(6)
	v_lshl_add_u32 v4, v16, 11, v4
	v_and_b32_e32 v5, 1, v15
	v_lshl_or_b32 v4, v5, 6, v4
	s_cselect_b64 s[8:9], -1, 0
	v_mov_b32_e32 v139, v2
	v_lshl_add_u32 v140, v17, 1, v4
	v_mov_b32_e32 v141, v2
	s_mov_b32 s45, 0
	v_add_u32_e32 v153, 0, v7
	s_barrier
	s_branch .LBB0_839
